# allstack: v111 + samplebegin fixhoist6 fixhoist7 fixhoist9 scalemerge xloopdpp tabbatch:late scanpfwait lastpf (every validated latency de-serialisation that measured neutral alone)
# baseline (speedup 1.0000x reference)
.LBB0_1017:
	v_pk_mul_f32 v[90:91], v[100:101], s[24:25] op_sel_hi:[1,0]
	v_pk_mul_f32 v[94:95], v[104:105], s[24:25] op_sel_hi:[1,0]
	v_pk_fma_f32 v[90:91], v[100:101], v[90:91], 1.0 op_sel_hi:[1,1,0]
	v_pk_mul_f32 v[96:97], v[102:103], s[24:25] op_sel_hi:[1,0]
	v_pk_mul_f32 v[92:93], v[98:99], s[24:25] op_sel_hi:[1,0]
	v_pk_mul_f32 v[90:91], v[100:101], v[90:91]
	v_pk_fma_f32 v[94:95], v[104:105], v[94:95], 1.0 op_sel_hi:[1,1,0]
	v_pk_fma_f32 v[96:97], v[102:103], v[96:97], 1.0 op_sel_hi:[1,1,0]
	v_pk_fma_f32 v[92:93], v[98:99], v[92:93], 1.0 op_sel_hi:[1,1,0]
	v_pk_mul_f32 v[94:95], v[104:105], v[94:95]
	v_pk_mul_f32 v[96:97], v[102:103], v[96:97]
	v_mul_f32_e32 v90, 0xc0135761, v90
	v_pk_mul_f32 v[92:93], v[98:99], v[92:93]
	v_mul_f32_e32 v96, 0xc0135761, v96
	v_exp_f32_e32 v106, v90
	v_mul_f32_e32 v90, 0xc0135761, v94
	v_mul_f32_e32 v92, 0xc0135761, v92
	v_exp_f32_e32 v96, v96
	v_mul_f32_e32 v93, 0xc0135761, v93
	v_exp_f32_e32 v107, v90
	v_mul_f32_e32 v90, 0xc0135761, v91
	v_exp_f32_e32 v92, v92
	v_exp_f32_e32 v93, v93
	v_mul_f32_e32 v97, 0xc0135761, v97
	v_exp_f32_e32 v108, v90
	v_mul_f32_e32 v90, 0xc0135761, v95
	v_exp_f32_e32 v97, v97
	v_exp_f32_e32 v109, v90
	v_add_f32_e32 v91, 1.0, v96
	v_add_f32_e32 v90, 1.0, v92
	v_rcp_f32_e32 v92, v91
	v_add_f32_e32 v91, 1.0, v93
	v_add_f32_e32 v95, 1.0, v107
	s_add_u32 s6, s26, s30
	v_rcp_f32_e32 v90, v90
	v_rcp_f32_e32 v91, v91
	v_add_f32_e32 v93, 1.0, v97
	v_add_f32_e32 v94, 1.0, v106
	v_rcp_f32_e32 v96, v95
	v_add_f32_e32 v95, 1.0, v108
	v_add_f32_e32 v97, 1.0, v109
	s_addc_u32 s7, s27, 0
	v_rcp_f32_e32 v94, v94
	v_rcp_f32_e32 v95, v95
	v_rcp_f32_e32 v97, v97
	v_rcp_f32_e32 v93, v93
	s_lshl_b64 s[6:7], s[6:7], 5
	s_add_u32 s6, s4, s6
	s_addc_u32 s7, s5, s7
	s_lshl_b32 s2, s2, 5
	v_pk_mul_f32 v[90:91], v[98:99], v[90:91]
	v_pk_mul_f32 v[94:95], v[100:101], v[94:95]
	v_pk_mul_f32 v[96:97], v[104:105], v[96:97]
	v_pk_mul_f32 v[92:93], v[102:103], v[92:93]
	v_cvt_pk_bf16_f32 v90, v90, v91
	v_cvt_pk_bf16_f32 v91, v94, v95
	v_add3_u32 v98, v214, s2, v210
	v_cvt_pk_bf16_f32 v92, v92, v93
	v_cvt_pk_bf16_f32 v93, v96, v97
	ds_write_b64 v98, v[90:91]
	ds_write_b64 v98, v[92:93] offset:8448
	v_pk_mul_f32 v[90:91], v[88:89], s[24:25] op_sel_hi:[1,0]
	v_pk_mul_f32 v[96:97], v[82:83], s[24:25] op_sel_hi:[1,0]
	v_pk_mul_f32 v[92:93], v[86:87], s[24:25] op_sel_hi:[1,0]
	v_pk_fma_f32 v[90:91], v[88:89], v[90:91], 1.0 op_sel_hi:[1,1,0]
	v_pk_mul_f32 v[94:95], v[84:85], s[24:25] op_sel_hi:[1,0]
	v_pk_fma_f32 v[96:97], v[82:83], v[96:97], 1.0 op_sel_hi:[1,1,0]
	v_pk_fma_f32 v[92:93], v[86:87], v[92:93], 1.0 op_sel_hi:[1,1,0]
	v_pk_mul_f32 v[90:91], v[88:89], v[90:91]
	v_pk_fma_f32 v[94:95], v[84:85], v[94:95], 1.0 op_sel_hi:[1,1,0]
	v_pk_mul_f32 v[96:97], v[82:83], v[96:97]
	v_pk_mul_f32 v[92:93], v[86:87], v[92:93]
	v_pk_mul_f32 v[94:95], v[84:85], v[94:95]
	v_mul_f32_e32 v96, 0xc0135761, v96
	v_mul_f32_e32 v90, 0xc0135761, v90
	v_mul_f32_e32 v92, 0xc0135761, v92
	v_exp_f32_e32 v96, v96
	v_mul_f32_e32 v93, 0xc0135761, v93
	v_exp_f32_e32 v99, v90
	v_mul_f32_e32 v90, 0xc0135761, v94
	v_exp_f32_e32 v92, v92
	v_exp_f32_e32 v93, v93
	v_mul_f32_e32 v97, 0xc0135761, v97
	v_exp_f32_e32 v100, v90
	v_mul_f32_e32 v90, 0xc0135761, v91
	v_exp_f32_e32 v97, v97
	v_exp_f32_e32 v101, v90
	v_mul_f32_e32 v90, 0xc0135761, v95
	v_exp_f32_e32 v102, v90
	v_add_f32_e32 v91, 1.0, v96
	v_add_f32_e32 v90, 1.0, v92
	v_rcp_f32_e32 v92, v91
	v_add_f32_e32 v91, 1.0, v93
	v_add_f32_e32 v95, 1.0, v100
	v_rcp_f32_e32 v90, v90
	v_rcp_f32_e32 v91, v91
	v_add_f32_e32 v93, 1.0, v97
	v_add_f32_e32 v94, 1.0, v99
	v_rcp_f32_e32 v96, v95
	v_add_f32_e32 v95, 1.0, v101
	v_rcp_f32_e32 v94, v94
	v_rcp_f32_e32 v95, v95
	v_add_f32_e32 v97, 1.0, v102
	v_rcp_f32_e32 v93, v93
	v_rcp_f32_e32 v97, v97
	v_pk_mul_f32 v[86:87], v[86:87], v[90:91]
	v_pk_mul_f32 v[88:89], v[88:89], v[94:95]
	v_pk_mul_f32 v[82:83], v[82:83], v[92:93]
	v_cvt_pk_bf16_f32 v86, v86, v87
	v_cvt_pk_bf16_f32 v87, v88, v89
	v_pk_mul_f32 v[84:85], v[84:85], v[96:97]
	v_cvt_pk_bf16_f32 v82, v82, v83
	v_lshl_add_u64 v[90:91], s[6:7], 0, v[168:169]
	v_cvt_pk_bf16_f32 v83, v84, v85
	ds_write_b64 v98, v[86:87] offset:16896
	ds_write_b64 v98, v[82:83] offset:25344
	s_waitcnt lgkmcnt(0)
	s_barrier
	v_add_u32_e32 v82, v215, v204
	ds_read_b128 v[82:85], v82
	v_add_u32_e32 v86, v215, v205
	ds_read_b128 v[86:89], v86
	v_add_u32_e32 v102, v215, v206
	ds_read_b128 v[102:105], v102
	v_add_u32_e32 v106, v215, v207
	ds_read_b128 v[106:109], v106
	v_add_co_u32_e32 v92, vcc, s12, v90
	v_addc_co_u32_e32 v93, vcc, 0, v91, vcc
	v_add_co_u32_e32 v94, vcc, 0x6000, v90
	v_addc_co_u32_e32 v95, vcc, 0, v91, vcc
	s_andn2_b64 vcc, exec, s[28:29]
	s_waitcnt lgkmcnt(3)
	global_store_dwordx4 v168, v[82:85], s[6:7]
	s_waitcnt lgkmcnt(2)
	global_store_dwordx4 v[92:93], v[86:89], off
	s_waitcnt lgkmcnt(1)
	global_store_dwordx4 v219, v[102:105], s[6:7]
	s_waitcnt lgkmcnt(0)
	global_store_dwordx4 v[94:95], v[106:109], off
	s_cbranch_vccnz .LBB0_1003
	s_waitcnt vmcnt(4)
	s_mul_i32 s38, s38, 0x8400
	v_add_u32_e32 v82, s38, v167
	v_add_u32_e32 v83, v82, v207
	v_add_u32_e32 v84, v82, v206
	v_add_u32_e32 v85, v82, v205
	v_add_u32_e32 v82, v82, v204
	ds_write_b128 v82, v[66:69]
	ds_write_b128 v85, v[70:73]
	ds_write_b128 v84, v[74:77]
	ds_write_b128 v83, v[78:81]
	s_branch .LBB0_1003
